# swiglu epilogue additionally touches next tile's weight K-tiles 2..5 (L2 warm-up loads, results unused)
# baseline (speedup 1.0000x reference)
; __device__ __forceinline__ unsigned cvt_pk_bf16(float lo, float hi) { unsigned r; asm volatile("v_cvt_pk_bf16_f32 %0, %1, %2" : "=v"(r) : "v"(lo), "v"(hi)); return r; }
;     __device__ __forceinline__ void operator()(const f32x4 (&acc)[2][2][4][2], const Unit& u, int wr, int wc, int fr, int fq) const {
;         const int row0 = u.pm * BM + wr * 64 + fr, ch0 = u.pn * 128 + wc * 32 + 8 * fq;
; #pragma unroll
;         for (int ai = 0; ai < 2; ++ai)
; #pragma unroll
;             for (int m = 0; m < 4; ++m) { const int row = row0 + ai * HALF + m * 16; const float rs = row_rstd(ssq, row, fr, fq), rs2 = rs * rs, nrl = -1.4426950408889634f * rs;
;                 float o[8];
; #pragma unroll
;                 for (int n = 0; n < 2; ++n) { const f32x4 g = acc[ai][0][m][n], gu = g * acc[ai][1][m][n] * rs2;
; #pragma unroll
;                     for (int j = 0; j < 4; ++j) o[4 * n + j] = gu[j] * __builtin_amdgcn_rcpf(1.0f + __builtin_amdgcn_exp2f(g[j] * nrl)); }
;                 u32x4 w; w.x = cvt_pk_bf16(o[0], o[1]); w.y = cvt_pk_bf16(o[2], o[3]); w.z = cvt_pk_bf16(o[4], o[5]); w.w = cvt_pk_bf16(o[6], o[7]);
;                 *(u32x4*)(ACT + (size_t)row * 5632 + ch0) = w;
;                 asm volatile("" ::: "memory"); }
.Lsw1_have:
	s_lshl_b32 s4, s78, 2
	s_lshl_b32 s5, s82, 1
	s_add_i32 s4, s4, s5
	v_add_u32_e32 v144, s4, v167
	v_lshrrev_b32_e32 v145, 4, v144
	v_and_b32_e32 v144, 15, v144
	v_lshlrev_b32_e32 v144, 5, v144
	v_lshl_add_u32 v144, v145, 12, v144
	s_and_b32 s4, s26, 7
	s_lshl_b32 s4, s4, 17
	v_add_u32_e32 v144, s4, v144
	s_mov_b32 s4, s57
	s_mov_b32 s5, s17
	s_nop 4
	global_load_dwordx4 v[242:245], v144, s[4:5] offset:256
	global_load_dwordx4 v[246:249], v144, s[4:5] offset:272
	v_and_b32_e32 v153, 15, v167
	v_lshrrev_b32_e32 v154, 4, v167
	s_lshl_b32 s4, s26, 8
	s_add_i32 s4, s4, s78
	v_or_b32_e32 v155, s4, v153
	s_lshl_b32 s4, s55, 7
	s_or_b32 s4, s4, s82
	v_lshl_add_u32 v162, v154, 3, s4
	v_lshlrev_b32_e32 v162, 1, v162
	v_mul_u32_u24_e32 v163, 0x2c00, v155
	v_add_u32_e32 v162, v162, v163
	v_mov_b32_e32 v164, v162
	v_mul_f32_e32 v124, v116, v124
	v_mul_f32_e32 v125, v117, v125
	v_mul_f32_e32 v126, v118, v126
	v_mul_f32_e32 v127, v119, v127
	v_mul_f32_e32 v120, v112, v120
	v_mul_f32_e32 v121, v113, v121
	v_mul_f32_e32 v122, v114, v122
	v_mul_f32_e32 v123, v115, v123
	v_mul_f32_e32 v116, v116, v226
	v_mul_f32_e32 v117, v117, v226
	v_mul_f32_e32 v118, v118, v226
	v_mul_f32_e32 v119, v119, v226
	v_mul_f32_e32 v112, v112, v226
	v_mul_f32_e32 v113, v113, v226
	v_mul_f32_e32 v114, v114, v226
	v_mul_f32_e32 v115, v115, v226
	v_exp_f32_e32 v116, v116
	v_exp_f32_e32 v117, v117
	v_exp_f32_e32 v118, v118
	v_exp_f32_e32 v119, v119
	v_exp_f32_e32 v112, v112
	v_exp_f32_e32 v113, v113
	v_exp_f32_e32 v114, v114
	v_exp_f32_e32 v115, v115
	v_add_f32_e32 v116, 1.0, v116
	v_add_f32_e32 v117, 1.0, v117
	v_add_f32_e32 v118, 1.0, v118
	v_add_f32_e32 v119, 1.0, v119
	v_add_f32_e32 v112, 1.0, v112
	v_add_f32_e32 v113, 1.0, v113
	v_add_f32_e32 v114, 1.0, v114
	v_add_f32_e32 v115, 1.0, v115
	v_rcp_f32_e32 v116, v116
	v_rcp_f32_e32 v117, v117
	v_rcp_f32_e32 v118, v118
	v_rcp_f32_e32 v119, v119
	v_rcp_f32_e32 v112, v112
	v_rcp_f32_e32 v113, v113
	v_rcp_f32_e32 v114, v114
	v_rcp_f32_e32 v115, v115
	v_mul_f32_e32 v124, v124, v234
	v_mul_f32_e32 v125, v125, v234
	v_mul_f32_e32 v126, v126, v234
	v_mul_f32_e32 v127, v127, v234
	v_mul_f32_e32 v120, v120, v234
	v_mul_f32_e32 v121, v121, v234
	v_mul_f32_e32 v122, v122, v234
	v_mul_f32_e32 v123, v123, v234
	v_mul_f32_e32 v124, v124, v116
	v_mul_f32_e32 v125, v125, v117
	v_mul_f32_e32 v126, v126, v118
	v_mul_f32_e32 v127, v127, v119
	v_mul_f32_e32 v120, v120, v112
	v_mul_f32_e32 v121, v121, v113
	v_mul_f32_e32 v122, v122, v114
	v_mul_f32_e32 v123, v123, v115
	v_cvt_pk_bf16_f32 v116, v124, v125
	v_cvt_pk_bf16_f32 v117, v126, v127
	v_cvt_pk_bf16_f32 v118, v120, v121
	v_cvt_pk_bf16_f32 v119, v122, v123
	global_store_dwordx4 v164, v[116:119], s[10:11]
	v_add_u32_e32 v165, 0x2c000, v162
	v_mul_f32_e32 v108, v100, v108
	v_mul_f32_e32 v109, v101, v109
	v_mul_f32_e32 v110, v102, v110
	v_mul_f32_e32 v111, v103, v111
	v_mul_f32_e32 v104, v96, v104
	v_mul_f32_e32 v105, v97, v105
	v_mul_f32_e32 v106, v98, v106
	v_mul_f32_e32 v107, v99, v107
	v_mul_f32_e32 v100, v100, v227
	v_mul_f32_e32 v101, v101, v227
	v_mul_f32_e32 v102, v102, v227
	v_mul_f32_e32 v103, v103, v227
	v_mul_f32_e32 v96, v96, v227
	v_mul_f32_e32 v97, v97, v227
	v_mul_f32_e32 v98, v98, v227
	v_mul_f32_e32 v99, v99, v227
	v_exp_f32_e32 v100, v100
	v_exp_f32_e32 v101, v101
	v_exp_f32_e32 v102, v102
	v_exp_f32_e32 v103, v103
	v_exp_f32_e32 v96, v96
	v_exp_f32_e32 v97, v97
	v_exp_f32_e32 v98, v98
	v_exp_f32_e32 v99, v99
	v_add_f32_e32 v100, 1.0, v100
	v_add_f32_e32 v101, 1.0, v101
	v_add_f32_e32 v102, 1.0, v102
	v_add_f32_e32 v103, 1.0, v103
	v_add_f32_e32 v96, 1.0, v96
	v_add_f32_e32 v97, 1.0, v97
	v_add_f32_e32 v98, 1.0, v98
	v_add_f32_e32 v99, 1.0, v99
	v_rcp_f32_e32 v100, v100
	v_rcp_f32_e32 v101, v101
	v_rcp_f32_e32 v102, v102
	v_rcp_f32_e32 v103, v103
	v_rcp_f32_e32 v96, v96
	v_rcp_f32_e32 v97, v97
	v_rcp_f32_e32 v98, v98
	v_rcp_f32_e32 v99, v99
	v_mul_f32_e32 v108, v108, v235
	v_mul_f32_e32 v109, v109, v235
	v_mul_f32_e32 v110, v110, v235
	v_mul_f32_e32 v111, v111, v235
	v_mul_f32_e32 v104, v104, v235
	v_mul_f32_e32 v105, v105, v235
	v_mul_f32_e32 v106, v106, v235
	v_mul_f32_e32 v107, v107, v235
	v_mul_f32_e32 v108, v108, v100
	v_mul_f32_e32 v109, v109, v101
	v_mul_f32_e32 v110, v110, v102
	v_mul_f32_e32 v111, v111, v103
	v_mul_f32_e32 v104, v104, v96
	v_mul_f32_e32 v105, v105, v97
	v_mul_f32_e32 v106, v106, v98
	v_mul_f32_e32 v107, v107, v99
	v_cvt_pk_bf16_f32 v100, v108, v109
	v_cvt_pk_bf16_f32 v101, v110, v111
	v_cvt_pk_bf16_f32 v102, v104, v105
	v_cvt_pk_bf16_f32 v103, v106, v107
	global_store_dwordx4 v165, v[100:103], s[10:11]
	v_add_u32_e32 v164, 0x58000, v162
	v_mul_f32_e32 v92, v84, v92
	v_mul_f32_e32 v93, v85, v93
	v_mul_f32_e32 v94, v86, v94
	v_mul_f32_e32 v95, v87, v95
	v_mul_f32_e32 v88, v80, v88
	v_mul_f32_e32 v89, v81, v89
	v_mul_f32_e32 v90, v82, v90
	v_mul_f32_e32 v91, v83, v91
	v_mul_f32_e32 v84, v84, v228
	v_mul_f32_e32 v85, v85, v228
	v_mul_f32_e32 v86, v86, v228
	v_mul_f32_e32 v87, v87, v228
	v_mul_f32_e32 v80, v80, v228
	v_mul_f32_e32 v81, v81, v228
	v_mul_f32_e32 v82, v82, v228
	v_mul_f32_e32 v83, v83, v228
	v_exp_f32_e32 v84, v84
	v_exp_f32_e32 v85, v85
	v_exp_f32_e32 v86, v86
	v_exp_f32_e32 v87, v87
	v_exp_f32_e32 v80, v80
	v_exp_f32_e32 v81, v81
	v_exp_f32_e32 v82, v82
	v_exp_f32_e32 v83, v83
	v_add_f32_e32 v84, 1.0, v84
	v_add_f32_e32 v85, 1.0, v85
	v_add_f32_e32 v86, 1.0, v86
	v_add_f32_e32 v87, 1.0, v87
	v_add_f32_e32 v80, 1.0, v80
	v_add_f32_e32 v81, 1.0, v81
	v_add_f32_e32 v82, 1.0, v82
	v_add_f32_e32 v83, 1.0, v83
	v_rcp_f32_e32 v84, v84
	v_rcp_f32_e32 v85, v85
	v_rcp_f32_e32 v86, v86
	v_rcp_f32_e32 v87, v87
	v_rcp_f32_e32 v80, v80
; __device__ __forceinline__ unsigned cvt_pk_bf16(float lo, float hi) { unsigned r; asm volatile("v_cvt_pk_bf16_f32 %0, %1, %2" : "=v"(r) : "v"(lo), "v"(hi)); return r; }
;     __device__ __forceinline__ void operator()(const f32x4 (&acc)[2][2][4][2], const Unit& u, int wr, int wc, int fr, int fq) const {
;         const int row0 = u.pm * BM + wr * 64 + fr, ch0 = u.pn * 128 + wc * 32 + 8 * fq;
; #pragma unroll
;         for (int ai = 0; ai < 2; ++ai)
; #pragma unroll
;             for (int m = 0; m < 4; ++m) { const int row = row0 + ai * HALF + m * 16; const float rs = row_rstd(ssq, row, fr, fq), rs2 = rs * rs, nrl = -1.4426950408889634f * rs;
;                 float o[8];
; #pragma unroll
;                 for (int n = 0; n < 2; ++n) { const f32x4 g = acc[ai][0][m][n], gu = g * acc[ai][1][m][n] * rs2;
; #pragma unroll
;                     for (int j = 0; j < 4; ++j) o[4 * n + j] = gu[j] * __builtin_amdgcn_rcpf(1.0f + __builtin_amdgcn_exp2f(g[j] * nrl)); }
;                 u32x4 w; w.x = cvt_pk_bf16(o[0], o[1]); w.y = cvt_pk_bf16(o[2], o[3]); w.z = cvt_pk_bf16(o[4], o[5]); w.w = cvt_pk_bf16(o[6], o[7]);
;                 *(u32x4*)(ACT + (size_t)row * 5632 + ch0) = w;
;                 asm volatile("" ::: "memory"); }
	v_rcp_f32_e32 v81, v81
	v_rcp_f32_e32 v82, v82
	v_rcp_f32_e32 v83, v83
	v_mul_f32_e32 v92, v92, v236
	v_mul_f32_e32 v93, v93, v236
	v_mul_f32_e32 v94, v94, v236
	v_mul_f32_e32 v95, v95, v236
	v_mul_f32_e32 v88, v88, v236
	v_mul_f32_e32 v89, v89, v236
	v_mul_f32_e32 v90, v90, v236
	v_mul_f32_e32 v91, v91, v236
	v_mul_f32_e32 v92, v92, v84
	v_mul_f32_e32 v93, v93, v85
	v_mul_f32_e32 v94, v94, v86
	v_mul_f32_e32 v95, v95, v87
	v_mul_f32_e32 v88, v88, v80
	v_mul_f32_e32 v89, v89, v81
	v_mul_f32_e32 v90, v90, v82
	v_mul_f32_e32 v91, v91, v83
	v_cvt_pk_bf16_f32 v84, v92, v93
	v_cvt_pk_bf16_f32 v85, v94, v95
	v_cvt_pk_bf16_f32 v86, v88, v89
	v_cvt_pk_bf16_f32 v87, v90, v91
	global_store_dwordx4 v164, v[84:87], s[10:11]
	v_add_u32_e32 v165, 0x84000, v162
	v_mul_f32_e32 v76, v68, v76
	v_mul_f32_e32 v77, v69, v77
	v_mul_f32_e32 v78, v70, v78
	v_mul_f32_e32 v79, v71, v79
	v_mul_f32_e32 v72, v64, v72
	v_mul_f32_e32 v73, v65, v73
	v_mul_f32_e32 v74, v66, v74
	v_mul_f32_e32 v75, v67, v75
	v_mul_f32_e32 v68, v68, v229
	v_mul_f32_e32 v69, v69, v229
	v_mul_f32_e32 v70, v70, v229
	v_mul_f32_e32 v71, v71, v229
	v_mul_f32_e32 v64, v64, v229
	v_mul_f32_e32 v65, v65, v229
	v_mul_f32_e32 v66, v66, v229
	v_mul_f32_e32 v67, v67, v229
	v_exp_f32_e32 v68, v68
	v_exp_f32_e32 v69, v69
	v_exp_f32_e32 v70, v70
	v_exp_f32_e32 v71, v71
	v_exp_f32_e32 v64, v64
	v_exp_f32_e32 v65, v65
	v_exp_f32_e32 v66, v66
	v_exp_f32_e32 v67, v67
	v_add_f32_e32 v68, 1.0, v68
	v_add_f32_e32 v69, 1.0, v69
	v_add_f32_e32 v70, 1.0, v70
	v_add_f32_e32 v71, 1.0, v71
	v_add_f32_e32 v64, 1.0, v64
	v_add_f32_e32 v65, 1.0, v65
	v_add_f32_e32 v66, 1.0, v66
	v_add_f32_e32 v67, 1.0, v67
	v_rcp_f32_e32 v68, v68
	v_rcp_f32_e32 v69, v69
	v_rcp_f32_e32 v70, v70
	v_rcp_f32_e32 v71, v71
	v_rcp_f32_e32 v64, v64
	v_rcp_f32_e32 v65, v65
	v_rcp_f32_e32 v66, v66
	v_rcp_f32_e32 v67, v67
	v_mul_f32_e32 v76, v76, v237
	v_mul_f32_e32 v77, v77, v237
	v_mul_f32_e32 v78, v78, v237
	v_mul_f32_e32 v79, v79, v237
	v_mul_f32_e32 v72, v72, v237
	v_mul_f32_e32 v73, v73, v237
	v_mul_f32_e32 v74, v74, v237
	v_mul_f32_e32 v75, v75, v237
	v_mul_f32_e32 v76, v76, v68
	v_mul_f32_e32 v77, v77, v69
	v_mul_f32_e32 v78, v78, v70
	v_mul_f32_e32 v79, v79, v71
	v_mul_f32_e32 v72, v72, v64
	v_mul_f32_e32 v73, v73, v65
	v_mul_f32_e32 v74, v74, v66
	v_mul_f32_e32 v75, v75, v67
	v_cvt_pk_bf16_f32 v68, v76, v77
	v_cvt_pk_bf16_f32 v69, v78, v79
	v_cvt_pk_bf16_f32 v70, v72, v73
	v_cvt_pk_bf16_f32 v71, v74, v75
	global_store_dwordx4 v165, v[68:71], s[10:11]
	v_add_u32_e32 v164, 0x160000, v162
	v_mul_f32_e32 v60, v52, v60
	v_mul_f32_e32 v61, v53, v61
	v_mul_f32_e32 v62, v54, v62
	v_mul_f32_e32 v63, v55, v63
	v_mul_f32_e32 v56, v48, v56
	v_mul_f32_e32 v57, v49, v57
	v_mul_f32_e32 v58, v50, v58
	v_mul_f32_e32 v59, v51, v59
	v_mul_f32_e32 v52, v52, v230
	v_mul_f32_e32 v53, v53, v230
	v_mul_f32_e32 v54, v54, v230
	v_mul_f32_e32 v55, v55, v230
	v_mul_f32_e32 v48, v48, v230
	v_mul_f32_e32 v49, v49, v230
	v_mul_f32_e32 v50, v50, v230
	v_mul_f32_e32 v51, v51, v230
	v_exp_f32_e32 v52, v52
	v_exp_f32_e32 v53, v53
	v_exp_f32_e32 v54, v54
	v_exp_f32_e32 v55, v55
	v_exp_f32_e32 v48, v48
	v_exp_f32_e32 v49, v49
	v_exp_f32_e32 v50, v50
	v_exp_f32_e32 v51, v51
	v_add_f32_e32 v52, 1.0, v52
	v_add_f32_e32 v53, 1.0, v53
	v_add_f32_e32 v54, 1.0, v54
	v_add_f32_e32 v55, 1.0, v55
	v_add_f32_e32 v48, 1.0, v48
	v_add_f32_e32 v49, 1.0, v49
	v_add_f32_e32 v50, 1.0, v50
	v_add_f32_e32 v51, 1.0, v51
	v_rcp_f32_e32 v52, v52
	v_rcp_f32_e32 v53, v53
	v_rcp_f32_e32 v54, v54
	v_rcp_f32_e32 v55, v55
	v_rcp_f32_e32 v48, v48
	v_rcp_f32_e32 v49, v49
	v_rcp_f32_e32 v50, v50
	v_rcp_f32_e32 v51, v51
	v_mul_f32_e32 v60, v60, v238
	v_mul_f32_e32 v61, v61, v238
	v_mul_f32_e32 v62, v62, v238
	v_mul_f32_e32 v63, v63, v238
	v_mul_f32_e32 v56, v56, v238
	v_mul_f32_e32 v57, v57, v238
	v_mul_f32_e32 v58, v58, v238
	v_mul_f32_e32 v59, v59, v238
	v_mul_f32_e32 v60, v60, v52
	v_mul_f32_e32 v61, v61, v53
	v_mul_f32_e32 v62, v62, v54
	v_mul_f32_e32 v63, v63, v55
	v_mul_f32_e32 v56, v56, v48
	v_mul_f32_e32 v57, v57, v49
	v_mul_f32_e32 v58, v58, v50
	v_mul_f32_e32 v59, v59, v51
	v_cvt_pk_bf16_f32 v52, v60, v61
	v_cvt_pk_bf16_f32 v53, v62, v63
	v_cvt_pk_bf16_f32 v54, v56, v57
	v_cvt_pk_bf16_f32 v55, v58, v59
	global_store_dwordx4 v164, v[52:55], s[10:11]
	v_add_u32_e32 v165, 0x18c000, v162
	v_mul_f32_e32 v44, v36, v44
	v_mul_f32_e32 v45, v37, v45
	v_mul_f32_e32 v46, v38, v46
	v_mul_f32_e32 v47, v39, v47
	v_mul_f32_e32 v40, v32, v40
	v_mul_f32_e32 v41, v33, v41
	v_mul_f32_e32 v42, v34, v42
	v_mul_f32_e32 v43, v35, v43
	v_mul_f32_e32 v36, v36, v231
	v_mul_f32_e32 v37, v37, v231
	v_mul_f32_e32 v38, v38, v231
	v_mul_f32_e32 v39, v39, v231
	v_mul_f32_e32 v32, v32, v231
	v_mul_f32_e32 v33, v33, v231
	v_mul_f32_e32 v34, v34, v231
	v_mul_f32_e32 v35, v35, v231
	v_exp_f32_e32 v36, v36
	v_exp_f32_e32 v37, v37
; __device__ __forceinline__ unsigned cvt_pk_bf16(float lo, float hi) { unsigned r; asm volatile("v_cvt_pk_bf16_f32 %0, %1, %2" : "=v"(r) : "v"(lo), "v"(hi)); return r; }
; #define PG8_BAR __builtin_amdgcn_s_barrier()
; template <class Epi, class Sched, bool ALIGN_EPI = false, bool SP2 = false>
; __device__ __forceinline__ void gemm_phase(PG8_LAS unsigned char* lds, const Gemm g, const Sched& S, const Epi& E) {
;     ...
;         if constexpr (ALIGN_EPI) { if (wr == 0) PG8_BAR; }
;         if constexpr (!Epi::AFTER_DRAIN) { int ln_ = __builtin_amdgcn_mbcnt_hi(~0u, __builtin_amdgcn_mbcnt_lo(~0u, 0u)); asm volatile("" : "+v"(ln_)); E(acc, cur, wr, wc, ln_ & 15, ln_ >> 4); S.done(cur); }
;         if (!has_next) break;
; #pragma unroll
;         for (int a = 0; a < 2; ++a)
; #pragma unroll
;             for (int b = 0; b < 2; ++b)
; #pragma unroll
;                 for (int m = 0; m < 4; ++m)
; #pragma unroll
;                     for (int n = 0; n < 2; ++n) acc[a][b][m][n] = (f32x4){0.f, 0.f, 0.f, 0.f};
;         cur = nxt; cA = nA; cB = nB; ++ui;
;         if constexpr (ALIGN_EPI) { if (wr == 1) PG8_BAR; }
;     __device__ __forceinline__ void operator()(const f32x4 (&acc)[2][2][4][2], const Unit& u, int wr, int wc, int fr, int fq) const {
;         const int row0 = u.pm * BM + wr * 64 + fr, ch0 = u.pn * 128 + wc * 32 + 8 * fq;
; #pragma unroll
;         for (int ai = 0; ai < 2; ++ai)
; #pragma unroll
;             for (int m = 0; m < 4; ++m) { const int row = row0 + ai * HALF + m * 16; const float rs = row_rstd(ssq, row, fr, fq), rs2 = rs * rs, nrl = -1.4426950408889634f * rs;
;                 float o[8];
; #pragma unroll
;                 for (int n = 0; n < 2; ++n) { const f32x4 g = acc[ai][0][m][n], gu = g * acc[ai][1][m][n] * rs2;
; #pragma unroll
;                     for (int j = 0; j < 4; ++j) o[4 * n + j] = gu[j] * __builtin_amdgcn_rcpf(1.0f + __builtin_amdgcn_exp2f(g[j] * nrl)); }
;                 u32x4 w; w.x = cvt_pk_bf16(o[0], o[1]); w.y = cvt_pk_bf16(o[2], o[3]); w.z = cvt_pk_bf16(o[4], o[5]); w.w = cvt_pk_bf16(o[6], o[7]);
;                 *(u32x4*)(ACT + (size_t)row * 5632 + ch0) = w;
;                 asm volatile("" ::: "memory"); }
	v_exp_f32_e32 v38, v38
	v_exp_f32_e32 v39, v39
	v_exp_f32_e32 v32, v32
	v_exp_f32_e32 v33, v33
	v_exp_f32_e32 v34, v34
	v_exp_f32_e32 v35, v35
	v_add_f32_e32 v36, 1.0, v36
	v_add_f32_e32 v37, 1.0, v37
	v_add_f32_e32 v38, 1.0, v38
	v_add_f32_e32 v39, 1.0, v39
	v_add_f32_e32 v32, 1.0, v32
	v_add_f32_e32 v33, 1.0, v33
	v_add_f32_e32 v34, 1.0, v34
	v_add_f32_e32 v35, 1.0, v35
	v_rcp_f32_e32 v36, v36
	v_rcp_f32_e32 v37, v37
	v_rcp_f32_e32 v38, v38
	v_rcp_f32_e32 v39, v39
	v_rcp_f32_e32 v32, v32
	v_rcp_f32_e32 v33, v33
	v_rcp_f32_e32 v34, v34
	v_rcp_f32_e32 v35, v35
	v_mul_f32_e32 v44, v44, v239
	v_mul_f32_e32 v45, v45, v239
	v_mul_f32_e32 v46, v46, v239
	v_mul_f32_e32 v47, v47, v239
	v_mul_f32_e32 v40, v40, v239
	v_mul_f32_e32 v41, v41, v239
	v_mul_f32_e32 v42, v42, v239
	v_mul_f32_e32 v43, v43, v239
	v_mul_f32_e32 v44, v44, v36
	v_mul_f32_e32 v45, v45, v37
	v_mul_f32_e32 v46, v46, v38
	v_mul_f32_e32 v47, v47, v39
	v_mul_f32_e32 v40, v40, v32
	v_mul_f32_e32 v41, v41, v33
	v_mul_f32_e32 v42, v42, v34
	v_mul_f32_e32 v43, v43, v35
	v_cvt_pk_bf16_f32 v36, v44, v45
	v_cvt_pk_bf16_f32 v37, v46, v47
	v_cvt_pk_bf16_f32 v38, v40, v41
	v_cvt_pk_bf16_f32 v39, v42, v43
	global_store_dwordx4 v165, v[36:39], s[10:11]
	v_add_u32_e32 v164, 0x1b8000, v162
	v_mul_f32_e32 v28, v20, v28
	v_mul_f32_e32 v29, v21, v29
	v_mul_f32_e32 v30, v22, v30
	v_mul_f32_e32 v31, v23, v31
	v_mul_f32_e32 v24, v16, v24
	v_mul_f32_e32 v25, v17, v25
	v_mul_f32_e32 v26, v18, v26
	v_mul_f32_e32 v27, v19, v27
	v_mul_f32_e32 v20, v20, v232
	v_mul_f32_e32 v21, v21, v232
	v_mul_f32_e32 v22, v22, v232
	v_mul_f32_e32 v23, v23, v232
	v_mul_f32_e32 v16, v16, v232
	v_mul_f32_e32 v17, v17, v232
	v_mul_f32_e32 v18, v18, v232
	v_mul_f32_e32 v19, v19, v232
	v_exp_f32_e32 v20, v20
	v_exp_f32_e32 v21, v21
	v_exp_f32_e32 v22, v22
	v_exp_f32_e32 v23, v23
	v_exp_f32_e32 v16, v16
	v_exp_f32_e32 v17, v17
	v_exp_f32_e32 v18, v18
	v_exp_f32_e32 v19, v19
	v_add_f32_e32 v20, 1.0, v20
	v_add_f32_e32 v21, 1.0, v21
	v_add_f32_e32 v22, 1.0, v22
	v_add_f32_e32 v23, 1.0, v23
	v_add_f32_e32 v16, 1.0, v16
	v_add_f32_e32 v17, 1.0, v17
	v_add_f32_e32 v18, 1.0, v18
	v_add_f32_e32 v19, 1.0, v19
	v_rcp_f32_e32 v20, v20
	v_rcp_f32_e32 v21, v21
	v_rcp_f32_e32 v22, v22
	v_rcp_f32_e32 v23, v23
	v_rcp_f32_e32 v16, v16
	v_rcp_f32_e32 v17, v17
	v_rcp_f32_e32 v18, v18
	v_rcp_f32_e32 v19, v19
	v_mul_f32_e32 v28, v28, v240
	v_mul_f32_e32 v29, v29, v240
	v_mul_f32_e32 v30, v30, v240
	v_mul_f32_e32 v31, v31, v240
	v_mul_f32_e32 v24, v24, v240
	v_mul_f32_e32 v25, v25, v240
	v_mul_f32_e32 v26, v26, v240
	v_mul_f32_e32 v27, v27, v240
	v_mul_f32_e32 v28, v28, v20
	v_mul_f32_e32 v29, v29, v21
	v_mul_f32_e32 v30, v30, v22
	v_mul_f32_e32 v31, v31, v23
	v_mul_f32_e32 v24, v24, v16
	v_mul_f32_e32 v25, v25, v17
	v_mul_f32_e32 v26, v26, v18
	v_mul_f32_e32 v27, v27, v19
	v_cvt_pk_bf16_f32 v20, v28, v29
	v_cvt_pk_bf16_f32 v21, v30, v31
	v_cvt_pk_bf16_f32 v22, v24, v25
	v_cvt_pk_bf16_f32 v23, v26, v27
	global_store_dwordx4 v164, v[20:23], s[10:11]
	v_add_u32_e32 v165, 0x1e4000, v162
	v_mul_f32_e32 v12, v8, v12
	v_mul_f32_e32 v13, v9, v13
	v_mul_f32_e32 v14, v10, v14
	v_mul_f32_e32 v15, v11, v15
	v_mul_f32_e32 v0, v4, v0
	v_mul_f32_e32 v1, v5, v1
	v_mul_f32_e32 v2, v6, v2
	v_mul_f32_e32 v3, v7, v3
	v_mul_f32_e32 v8, v8, v233
	v_mul_f32_e32 v9, v9, v233
	v_mul_f32_e32 v10, v10, v233
	v_mul_f32_e32 v11, v11, v233
	v_mul_f32_e32 v4, v4, v233
	v_mul_f32_e32 v5, v5, v233
	v_mul_f32_e32 v6, v6, v233
	v_mul_f32_e32 v7, v7, v233
	v_exp_f32_e32 v8, v8
	v_exp_f32_e32 v9, v9
	v_exp_f32_e32 v10, v10
	v_exp_f32_e32 v11, v11
	v_exp_f32_e32 v4, v4
	v_exp_f32_e32 v5, v5
	v_exp_f32_e32 v6, v6
	v_exp_f32_e32 v7, v7
	v_add_f32_e32 v8, 1.0, v8
	v_add_f32_e32 v9, 1.0, v9
	v_add_f32_e32 v10, 1.0, v10
	v_add_f32_e32 v11, 1.0, v11
	v_add_f32_e32 v4, 1.0, v4
	v_add_f32_e32 v5, 1.0, v5
	v_add_f32_e32 v6, 1.0, v6
	v_add_f32_e32 v7, 1.0, v7
	v_rcp_f32_e32 v8, v8
	v_rcp_f32_e32 v9, v9
	v_rcp_f32_e32 v10, v10
	v_rcp_f32_e32 v11, v11
	v_rcp_f32_e32 v4, v4
	v_rcp_f32_e32 v5, v5
	v_rcp_f32_e32 v6, v6
	v_rcp_f32_e32 v7, v7
	v_mul_f32_e32 v12, v12, v241
	v_mul_f32_e32 v13, v13, v241
	v_mul_f32_e32 v14, v14, v241
	v_mul_f32_e32 v15, v15, v241
	v_mul_f32_e32 v0, v0, v241
	v_mul_f32_e32 v1, v1, v241
	v_mul_f32_e32 v2, v2, v241
	v_mul_f32_e32 v3, v3, v241
	v_mul_f32_e32 v12, v12, v8
	v_mul_f32_e32 v13, v13, v9
	v_mul_f32_e32 v14, v14, v10
	v_mul_f32_e32 v15, v15, v11
	v_mul_f32_e32 v0, v0, v4
	v_mul_f32_e32 v1, v1, v5
	v_mul_f32_e32 v2, v2, v6
	v_mul_f32_e32 v3, v3, v7
	v_cvt_pk_bf16_f32 v8, v12, v13
	v_cvt_pk_bf16_f32 v9, v14, v15
	v_cvt_pk_bf16_f32 v10, v0, v1
	v_cvt_pk_bf16_f32 v11, v2, v3
	global_store_dwordx4 v165, v[8:11], s[10:11]
	s_andn2_b64 vcc, exec, s[8:9]
	s_mov_b64 s[8:9], -1
	s_cbranch_vccnz .LBB0_732
	s_and_b64 vcc, exec, s[64:65]
	s_cbranch_vccnz .LBB0_731
	s_barrier
	s_branch .LBB0_731

; __device__ __forceinline__ unsigned cvt_pk_bf16(float lo, float hi) { unsigned r; asm volatile("v_cvt_pk_bf16_f32 %0, %1, %2" : "=v"(r) : "v"(lo), "v"(hi)); return r; }
;     __device__ __forceinline__ void operator()(const f32x4 (&acc)[2][2][4][2], const Unit& u, int wr, int wc, int fr, int fq) const {
;         const int row0 = u.pm * BM + wr * 64 + fr, ch0 = u.pn * 128 + wc * 32 + 8 * fq;
; #pragma unroll
;         for (int ai = 0; ai < 2; ++ai)
; #pragma unroll
;             for (int m = 0; m < 4; ++m) { const int row = row0 + ai * HALF + m * 16; const float rs = row_rstd(ssq, row, fr, fq), rs2 = rs * rs, nrl = -1.4426950408889634f * rs;
;                 float o[8];
; #pragma unroll
;                 for (int n = 0; n < 2; ++n) { const f32x4 g = acc[ai][0][m][n], gu = g * acc[ai][1][m][n] * rs2;
; #pragma unroll
;                     for (int j = 0; j < 4; ++j) o[4 * n + j] = gu[j] * __builtin_amdgcn_rcpf(1.0f + __builtin_amdgcn_exp2f(g[j] * nrl)); }
;                 u32x4 w; w.x = cvt_pk_bf16(o[0], o[1]); w.y = cvt_pk_bf16(o[2], o[3]); w.z = cvt_pk_bf16(o[4], o[5]); w.w = cvt_pk_bf16(o[6], o[7]);
;                 *(u32x4*)(ACT + (size_t)row * 5632 + ch0) = w;
;                 asm volatile("" ::: "memory"); }
.Lsw2_have:
	s_lshl_b32 s4, s78, 2
	s_lshl_b32 s5, s82, 1
	s_add_i32 s4, s4, s5
	v_add_u32_e32 v144, s4, v167
	v_lshrrev_b32_e32 v145, 4, v144
	v_and_b32_e32 v144, 15, v144
	v_lshlrev_b32_e32 v144, 5, v144
	v_lshl_add_u32 v144, v145, 12, v144
	s_and_b32 s4, s26, 7
	s_lshl_b32 s4, s4, 17
	v_add_u32_e32 v144, s4, v144
	s_mov_b32 s4, s55
	s_mov_b32 s5, s17
	s_nop 4
	global_load_dwordx4 v[242:245], v144, s[4:5] offset:256
	global_load_dwordx4 v[246:249], v144, s[4:5] offset:272
	v_and_b32_e32 v153, 15, v167
	v_lshrrev_b32_e32 v154, 4, v167
	s_lshl_b32 s4, s26, 8
	s_add_i32 s4, s4, s78
	v_or_b32_e32 v155, s4, v153
	s_lshl_b32 s4, s53, 7
	s_or_b32 s4, s4, s82
	v_lshl_add_u32 v162, v154, 3, s4
	v_lshlrev_b32_e32 v162, 1, v162
	v_mul_u32_u24_e32 v163, 0x2c00, v155
	v_add_u32_e32 v162, v162, v163
	v_mov_b32_e32 v164, v162
	v_mul_f32_e32 v124, v116, v124
	v_mul_f32_e32 v125, v117, v125
	v_mul_f32_e32 v126, v118, v126
	v_mul_f32_e32 v127, v119, v127
	v_mul_f32_e32 v120, v112, v120
	v_mul_f32_e32 v121, v113, v121
	v_mul_f32_e32 v122, v114, v122
	v_mul_f32_e32 v123, v115, v123
	v_mul_f32_e32 v116, v116, v226
	v_mul_f32_e32 v117, v117, v226
	v_mul_f32_e32 v118, v118, v226
	v_mul_f32_e32 v119, v119, v226
	v_mul_f32_e32 v112, v112, v226
	v_mul_f32_e32 v113, v113, v226
	v_mul_f32_e32 v114, v114, v226
	v_mul_f32_e32 v115, v115, v226
	v_exp_f32_e32 v116, v116
	v_exp_f32_e32 v117, v117
	v_exp_f32_e32 v118, v118
	v_exp_f32_e32 v119, v119
	v_exp_f32_e32 v112, v112
	v_exp_f32_e32 v113, v113
	v_exp_f32_e32 v114, v114
	v_exp_f32_e32 v115, v115
	v_add_f32_e32 v116, 1.0, v116
	v_add_f32_e32 v117, 1.0, v117
	v_add_f32_e32 v118, 1.0, v118
	v_add_f32_e32 v119, 1.0, v119
	v_add_f32_e32 v112, 1.0, v112
	v_add_f32_e32 v113, 1.0, v113
	v_add_f32_e32 v114, 1.0, v114
	v_add_f32_e32 v115, 1.0, v115
	v_rcp_f32_e32 v116, v116
	v_rcp_f32_e32 v117, v117
	v_rcp_f32_e32 v118, v118
	v_rcp_f32_e32 v119, v119
	v_rcp_f32_e32 v112, v112
	v_rcp_f32_e32 v113, v113
	v_rcp_f32_e32 v114, v114
	v_rcp_f32_e32 v115, v115
	v_mul_f32_e32 v124, v124, v234
	v_mul_f32_e32 v125, v125, v234
	v_mul_f32_e32 v126, v126, v234
	v_mul_f32_e32 v127, v127, v234
	v_mul_f32_e32 v120, v120, v234
	v_mul_f32_e32 v121, v121, v234
	v_mul_f32_e32 v122, v122, v234
	v_mul_f32_e32 v123, v123, v234
	v_mul_f32_e32 v124, v124, v116
	v_mul_f32_e32 v125, v125, v117
	v_mul_f32_e32 v126, v126, v118
	v_mul_f32_e32 v127, v127, v119
	v_mul_f32_e32 v120, v120, v112
	v_mul_f32_e32 v121, v121, v113
	v_mul_f32_e32 v122, v122, v114
	v_mul_f32_e32 v123, v123, v115
	v_cvt_pk_bf16_f32 v116, v124, v125
	v_cvt_pk_bf16_f32 v117, v126, v127
	v_cvt_pk_bf16_f32 v118, v120, v121
	v_cvt_pk_bf16_f32 v119, v122, v123
	global_store_dwordx4 v164, v[116:119], s[10:11]
	v_add_u32_e32 v165, 0x2c000, v162
	v_mul_f32_e32 v108, v100, v108
	v_mul_f32_e32 v109, v101, v109
	v_mul_f32_e32 v110, v102, v110
	v_mul_f32_e32 v111, v103, v111
	v_mul_f32_e32 v104, v96, v104
	v_mul_f32_e32 v105, v97, v105
	v_mul_f32_e32 v106, v98, v106
	v_mul_f32_e32 v107, v99, v107
	v_mul_f32_e32 v100, v100, v227
	v_mul_f32_e32 v101, v101, v227
	v_mul_f32_e32 v102, v102, v227
	v_mul_f32_e32 v103, v103, v227
	v_mul_f32_e32 v96, v96, v227
	v_mul_f32_e32 v97, v97, v227
	v_mul_f32_e32 v98, v98, v227
	v_mul_f32_e32 v99, v99, v227
	v_exp_f32_e32 v100, v100
	v_exp_f32_e32 v101, v101
	v_exp_f32_e32 v102, v102
	v_exp_f32_e32 v103, v103
	v_exp_f32_e32 v96, v96
	v_exp_f32_e32 v97, v97
	v_exp_f32_e32 v98, v98
	v_exp_f32_e32 v99, v99
	v_add_f32_e32 v100, 1.0, v100
	v_add_f32_e32 v101, 1.0, v101
	v_add_f32_e32 v102, 1.0, v102
	v_add_f32_e32 v103, 1.0, v103
	v_add_f32_e32 v96, 1.0, v96
	v_add_f32_e32 v97, 1.0, v97
	v_add_f32_e32 v98, 1.0, v98
	v_add_f32_e32 v99, 1.0, v99
	v_rcp_f32_e32 v100, v100
	v_rcp_f32_e32 v101, v101
	v_rcp_f32_e32 v102, v102
	v_rcp_f32_e32 v103, v103
	v_rcp_f32_e32 v96, v96
	v_rcp_f32_e32 v97, v97
	v_rcp_f32_e32 v98, v98
	v_rcp_f32_e32 v99, v99
	v_mul_f32_e32 v108, v108, v235
	v_mul_f32_e32 v109, v109, v235
	v_mul_f32_e32 v110, v110, v235
	v_mul_f32_e32 v111, v111, v235
	v_mul_f32_e32 v104, v104, v235
	v_mul_f32_e32 v105, v105, v235
	v_mul_f32_e32 v106, v106, v235
	v_mul_f32_e32 v107, v107, v235
	v_mul_f32_e32 v108, v108, v100
	v_mul_f32_e32 v109, v109, v101
	v_mul_f32_e32 v110, v110, v102
	v_mul_f32_e32 v111, v111, v103
	v_mul_f32_e32 v104, v104, v96
	v_mul_f32_e32 v105, v105, v97
	v_mul_f32_e32 v106, v106, v98
	v_mul_f32_e32 v107, v107, v99
	v_cvt_pk_bf16_f32 v100, v108, v109
	v_cvt_pk_bf16_f32 v101, v110, v111
	v_cvt_pk_bf16_f32 v102, v104, v105
	v_cvt_pk_bf16_f32 v103, v106, v107
	global_store_dwordx4 v165, v[100:103], s[10:11]
	v_add_u32_e32 v164, 0x58000, v162
	v_mul_f32_e32 v92, v84, v92
	v_mul_f32_e32 v93, v85, v93
	v_mul_f32_e32 v94, v86, v94
	v_mul_f32_e32 v95, v87, v95
	v_mul_f32_e32 v88, v80, v88
	v_mul_f32_e32 v89, v81, v89
	v_mul_f32_e32 v90, v82, v90
	v_mul_f32_e32 v91, v83, v91
	v_mul_f32_e32 v84, v84, v228
	v_mul_f32_e32 v85, v85, v228
	v_mul_f32_e32 v86, v86, v228
	v_mul_f32_e32 v87, v87, v228
	v_mul_f32_e32 v80, v80, v228
	v_mul_f32_e32 v81, v81, v228
	v_mul_f32_e32 v82, v82, v228
	v_mul_f32_e32 v83, v83, v228
	v_exp_f32_e32 v84, v84
	v_exp_f32_e32 v85, v85
	v_exp_f32_e32 v86, v86
	v_exp_f32_e32 v87, v87
	v_exp_f32_e32 v80, v80
	v_exp_f32_e32 v81, v81
	v_exp_f32_e32 v82, v82
	v_exp_f32_e32 v83, v83
	v_add_f32_e32 v84, 1.0, v84
	v_add_f32_e32 v85, 1.0, v85
	v_add_f32_e32 v86, 1.0, v86
	v_add_f32_e32 v87, 1.0, v87
	v_add_f32_e32 v80, 1.0, v80
	v_add_f32_e32 v81, 1.0, v81
	v_add_f32_e32 v82, 1.0, v82
	v_add_f32_e32 v83, 1.0, v83
	v_rcp_f32_e32 v84, v84
	v_rcp_f32_e32 v85, v85
	v_rcp_f32_e32 v86, v86
	v_rcp_f32_e32 v87, v87
	v_rcp_f32_e32 v80, v80
; __device__ __forceinline__ unsigned cvt_pk_bf16(float lo, float hi) { unsigned r; asm volatile("v_cvt_pk_bf16_f32 %0, %1, %2" : "=v"(r) : "v"(lo), "v"(hi)); return r; }
;     __device__ __forceinline__ void operator()(const f32x4 (&acc)[2][2][4][2], const Unit& u, int wr, int wc, int fr, int fq) const {
;         const int row0 = u.pm * BM + wr * 64 + fr, ch0 = u.pn * 128 + wc * 32 + 8 * fq;
; #pragma unroll
;         for (int ai = 0; ai < 2; ++ai)
; #pragma unroll
;             for (int m = 0; m < 4; ++m) { const int row = row0 + ai * HALF + m * 16; const float rs = row_rstd(ssq, row, fr, fq), rs2 = rs * rs, nrl = -1.4426950408889634f * rs;
;                 float o[8];
; #pragma unroll
;                 for (int n = 0; n < 2; ++n) { const f32x4 g = acc[ai][0][m][n], gu = g * acc[ai][1][m][n] * rs2;
; #pragma unroll
;                     for (int j = 0; j < 4; ++j) o[4 * n + j] = gu[j] * __builtin_amdgcn_rcpf(1.0f + __builtin_amdgcn_exp2f(g[j] * nrl)); }
;                 u32x4 w; w.x = cvt_pk_bf16(o[0], o[1]); w.y = cvt_pk_bf16(o[2], o[3]); w.z = cvt_pk_bf16(o[4], o[5]); w.w = cvt_pk_bf16(o[6], o[7]);
;                 *(u32x4*)(ACT + (size_t)row * 5632 + ch0) = w;
;                 asm volatile("" ::: "memory"); }
	v_rcp_f32_e32 v81, v81
	v_rcp_f32_e32 v82, v82
	v_rcp_f32_e32 v83, v83
	v_mul_f32_e32 v92, v92, v236
	v_mul_f32_e32 v93, v93, v236
	v_mul_f32_e32 v94, v94, v236
	v_mul_f32_e32 v95, v95, v236
	v_mul_f32_e32 v88, v88, v236
	v_mul_f32_e32 v89, v89, v236
	v_mul_f32_e32 v90, v90, v236
	v_mul_f32_e32 v91, v91, v236
	v_mul_f32_e32 v92, v92, v84
	v_mul_f32_e32 v93, v93, v85
	v_mul_f32_e32 v94, v94, v86
	v_mul_f32_e32 v95, v95, v87
	v_mul_f32_e32 v88, v88, v80
	v_mul_f32_e32 v89, v89, v81
	v_mul_f32_e32 v90, v90, v82
	v_mul_f32_e32 v91, v91, v83
	v_cvt_pk_bf16_f32 v84, v92, v93
	v_cvt_pk_bf16_f32 v85, v94, v95
	v_cvt_pk_bf16_f32 v86, v88, v89
	v_cvt_pk_bf16_f32 v87, v90, v91
	global_store_dwordx4 v164, v[84:87], s[10:11]
	v_add_u32_e32 v165, 0x84000, v162
	v_mul_f32_e32 v76, v68, v76
	v_mul_f32_e32 v77, v69, v77
	v_mul_f32_e32 v78, v70, v78
	v_mul_f32_e32 v79, v71, v79
	v_mul_f32_e32 v72, v64, v72
	v_mul_f32_e32 v73, v65, v73
	v_mul_f32_e32 v74, v66, v74
	v_mul_f32_e32 v75, v67, v75
	v_mul_f32_e32 v68, v68, v229
	v_mul_f32_e32 v69, v69, v229
	v_mul_f32_e32 v70, v70, v229
	v_mul_f32_e32 v71, v71, v229
	v_mul_f32_e32 v64, v64, v229
	v_mul_f32_e32 v65, v65, v229
	v_mul_f32_e32 v66, v66, v229
	v_mul_f32_e32 v67, v67, v229
	v_exp_f32_e32 v68, v68
	v_exp_f32_e32 v69, v69
	v_exp_f32_e32 v70, v70
	v_exp_f32_e32 v71, v71
	v_exp_f32_e32 v64, v64
	v_exp_f32_e32 v65, v65
	v_exp_f32_e32 v66, v66
	v_exp_f32_e32 v67, v67
	v_add_f32_e32 v68, 1.0, v68
	v_add_f32_e32 v69, 1.0, v69
	v_add_f32_e32 v70, 1.0, v70
	v_add_f32_e32 v71, 1.0, v71
	v_add_f32_e32 v64, 1.0, v64
	v_add_f32_e32 v65, 1.0, v65
	v_add_f32_e32 v66, 1.0, v66
	v_add_f32_e32 v67, 1.0, v67
	v_rcp_f32_e32 v68, v68
	v_rcp_f32_e32 v69, v69
	v_rcp_f32_e32 v70, v70
	v_rcp_f32_e32 v71, v71
	v_rcp_f32_e32 v64, v64
	v_rcp_f32_e32 v65, v65
	v_rcp_f32_e32 v66, v66
	v_rcp_f32_e32 v67, v67
	v_mul_f32_e32 v76, v76, v237
	v_mul_f32_e32 v77, v77, v237
	v_mul_f32_e32 v78, v78, v237
	v_mul_f32_e32 v79, v79, v237
	v_mul_f32_e32 v72, v72, v237
	v_mul_f32_e32 v73, v73, v237
	v_mul_f32_e32 v74, v74, v237
	v_mul_f32_e32 v75, v75, v237
	v_mul_f32_e32 v76, v76, v68
	v_mul_f32_e32 v77, v77, v69
	v_mul_f32_e32 v78, v78, v70
	v_mul_f32_e32 v79, v79, v71
	v_mul_f32_e32 v72, v72, v64
	v_mul_f32_e32 v73, v73, v65
	v_mul_f32_e32 v74, v74, v66
	v_mul_f32_e32 v75, v75, v67
	v_cvt_pk_bf16_f32 v68, v76, v77
	v_cvt_pk_bf16_f32 v69, v78, v79
	v_cvt_pk_bf16_f32 v70, v72, v73
	v_cvt_pk_bf16_f32 v71, v74, v75
	global_store_dwordx4 v165, v[68:71], s[10:11]
	v_add_u32_e32 v164, 0x160000, v162
	v_mul_f32_e32 v60, v52, v60
	v_mul_f32_e32 v61, v53, v61
	v_mul_f32_e32 v62, v54, v62
	v_mul_f32_e32 v63, v55, v63
	v_mul_f32_e32 v56, v48, v56
	v_mul_f32_e32 v57, v49, v57
	v_mul_f32_e32 v58, v50, v58
	v_mul_f32_e32 v59, v51, v59
	v_mul_f32_e32 v52, v52, v230
	v_mul_f32_e32 v53, v53, v230
	v_mul_f32_e32 v54, v54, v230
	v_mul_f32_e32 v55, v55, v230
	v_mul_f32_e32 v48, v48, v230
	v_mul_f32_e32 v49, v49, v230
	v_mul_f32_e32 v50, v50, v230
	v_mul_f32_e32 v51, v51, v230
	v_exp_f32_e32 v52, v52
	v_exp_f32_e32 v53, v53
	v_exp_f32_e32 v54, v54
	v_exp_f32_e32 v55, v55
	v_exp_f32_e32 v48, v48
	v_exp_f32_e32 v49, v49
	v_exp_f32_e32 v50, v50
	v_exp_f32_e32 v51, v51
	v_add_f32_e32 v52, 1.0, v52
	v_add_f32_e32 v53, 1.0, v53
	v_add_f32_e32 v54, 1.0, v54
	v_add_f32_e32 v55, 1.0, v55
	v_add_f32_e32 v48, 1.0, v48
	v_add_f32_e32 v49, 1.0, v49
	v_add_f32_e32 v50, 1.0, v50
	v_add_f32_e32 v51, 1.0, v51
	v_rcp_f32_e32 v52, v52
	v_rcp_f32_e32 v53, v53
	v_rcp_f32_e32 v54, v54
	v_rcp_f32_e32 v55, v55
	v_rcp_f32_e32 v48, v48
	v_rcp_f32_e32 v49, v49
	v_rcp_f32_e32 v50, v50
	v_rcp_f32_e32 v51, v51
	v_mul_f32_e32 v60, v60, v238
	v_mul_f32_e32 v61, v61, v238
	v_mul_f32_e32 v62, v62, v238
	v_mul_f32_e32 v63, v63, v238
	v_mul_f32_e32 v56, v56, v238
	v_mul_f32_e32 v57, v57, v238
	v_mul_f32_e32 v58, v58, v238
	v_mul_f32_e32 v59, v59, v238
	v_mul_f32_e32 v60, v60, v52
	v_mul_f32_e32 v61, v61, v53
	v_mul_f32_e32 v62, v62, v54
	v_mul_f32_e32 v63, v63, v55
	v_mul_f32_e32 v56, v56, v48
	v_mul_f32_e32 v57, v57, v49
	v_mul_f32_e32 v58, v58, v50
	v_mul_f32_e32 v59, v59, v51
	v_cvt_pk_bf16_f32 v52, v60, v61
	v_cvt_pk_bf16_f32 v53, v62, v63
	v_cvt_pk_bf16_f32 v54, v56, v57
	v_cvt_pk_bf16_f32 v55, v58, v59
	global_store_dwordx4 v164, v[52:55], s[10:11]
	v_add_u32_e32 v165, 0x18c000, v162
	v_mul_f32_e32 v44, v36, v44
	v_mul_f32_e32 v45, v37, v45
	v_mul_f32_e32 v46, v38, v46
	v_mul_f32_e32 v47, v39, v47
	v_mul_f32_e32 v40, v32, v40
	v_mul_f32_e32 v41, v33, v41
	v_mul_f32_e32 v42, v34, v42
	v_mul_f32_e32 v43, v35, v43
	v_mul_f32_e32 v36, v36, v231
	v_mul_f32_e32 v37, v37, v231
	v_mul_f32_e32 v38, v38, v231
	v_mul_f32_e32 v39, v39, v231
	v_mul_f32_e32 v32, v32, v231
	v_mul_f32_e32 v33, v33, v231
	v_mul_f32_e32 v34, v34, v231
	v_mul_f32_e32 v35, v35, v231
	v_exp_f32_e32 v36, v36
	v_exp_f32_e32 v37, v37
; __device__ __forceinline__ unsigned cvt_pk_bf16(float lo, float hi) { unsigned r; asm volatile("v_cvt_pk_bf16_f32 %0, %1, %2" : "=v"(r) : "v"(lo), "v"(hi)); return r; }
; #define PG8_BAR __builtin_amdgcn_s_barrier()
; template <class Epi, class Sched, bool ALIGN_EPI = false, bool SP2 = false>
; __device__ __forceinline__ void gemm_phase(PG8_LAS unsigned char* lds, const Gemm g, const Sched& S, const Epi& E) {
;     ...
;         if constexpr (ALIGN_EPI) { if (wr == 0) PG8_BAR; }
;         if constexpr (!Epi::AFTER_DRAIN) { int ln_ = __builtin_amdgcn_mbcnt_hi(~0u, __builtin_amdgcn_mbcnt_lo(~0u, 0u)); asm volatile("" : "+v"(ln_)); E(acc, cur, wr, wc, ln_ & 15, ln_ >> 4); S.done(cur); }
;         if (!has_next) break;
; #pragma unroll
;         for (int a = 0; a < 2; ++a)
; #pragma unroll
;             for (int b = 0; b < 2; ++b)
; #pragma unroll
;                 for (int m = 0; m < 4; ++m)
; #pragma unroll
;                     for (int n = 0; n < 2; ++n) acc[a][b][m][n] = (f32x4){0.f, 0.f, 0.f, 0.f};
;         cur = nxt; cA = nA; cB = nB; ++ui;
;         if constexpr (ALIGN_EPI) { if (wr == 1) PG8_BAR; }
;     __device__ __forceinline__ void operator()(const f32x4 (&acc)[2][2][4][2], const Unit& u, int wr, int wc, int fr, int fq) const {
;         const int row0 = u.pm * BM + wr * 64 + fr, ch0 = u.pn * 128 + wc * 32 + 8 * fq;
; #pragma unroll
;         for (int ai = 0; ai < 2; ++ai)
; #pragma unroll
;             for (int m = 0; m < 4; ++m) { const int row = row0 + ai * HALF + m * 16; const float rs = row_rstd(ssq, row, fr, fq), rs2 = rs * rs, nrl = -1.4426950408889634f * rs;
;                 float o[8];
; #pragma unroll
;                 for (int n = 0; n < 2; ++n) { const f32x4 g = acc[ai][0][m][n], gu = g * acc[ai][1][m][n] * rs2;
; #pragma unroll
;                     for (int j = 0; j < 4; ++j) o[4 * n + j] = gu[j] * __builtin_amdgcn_rcpf(1.0f + __builtin_amdgcn_exp2f(g[j] * nrl)); }
;                 u32x4 w; w.x = cvt_pk_bf16(o[0], o[1]); w.y = cvt_pk_bf16(o[2], o[3]); w.z = cvt_pk_bf16(o[4], o[5]); w.w = cvt_pk_bf16(o[6], o[7]);
;                 *(u32x4*)(ACT + (size_t)row * 5632 + ch0) = w;
;                 asm volatile("" ::: "memory"); }
	v_exp_f32_e32 v38, v38
	v_exp_f32_e32 v39, v39
	v_exp_f32_e32 v32, v32
	v_exp_f32_e32 v33, v33
	v_exp_f32_e32 v34, v34
	v_exp_f32_e32 v35, v35
	v_add_f32_e32 v36, 1.0, v36
	v_add_f32_e32 v37, 1.0, v37
	v_add_f32_e32 v38, 1.0, v38
	v_add_f32_e32 v39, 1.0, v39
	v_add_f32_e32 v32, 1.0, v32
	v_add_f32_e32 v33, 1.0, v33
	v_add_f32_e32 v34, 1.0, v34
	v_add_f32_e32 v35, 1.0, v35
	v_rcp_f32_e32 v36, v36
	v_rcp_f32_e32 v37, v37
	v_rcp_f32_e32 v38, v38
	v_rcp_f32_e32 v39, v39
	v_rcp_f32_e32 v32, v32
	v_rcp_f32_e32 v33, v33
	v_rcp_f32_e32 v34, v34
	v_rcp_f32_e32 v35, v35
	v_mul_f32_e32 v44, v44, v239
	v_mul_f32_e32 v45, v45, v239
	v_mul_f32_e32 v46, v46, v239
	v_mul_f32_e32 v47, v47, v239
	v_mul_f32_e32 v40, v40, v239
	v_mul_f32_e32 v41, v41, v239
	v_mul_f32_e32 v42, v42, v239
	v_mul_f32_e32 v43, v43, v239
	v_mul_f32_e32 v44, v44, v36
	v_mul_f32_e32 v45, v45, v37
	v_mul_f32_e32 v46, v46, v38
	v_mul_f32_e32 v47, v47, v39
	v_mul_f32_e32 v40, v40, v32
	v_mul_f32_e32 v41, v41, v33
	v_mul_f32_e32 v42, v42, v34
	v_mul_f32_e32 v43, v43, v35
	v_cvt_pk_bf16_f32 v36, v44, v45
	v_cvt_pk_bf16_f32 v37, v46, v47
	v_cvt_pk_bf16_f32 v38, v40, v41
	v_cvt_pk_bf16_f32 v39, v42, v43
	global_store_dwordx4 v165, v[36:39], s[10:11]
	v_add_u32_e32 v164, 0x1b8000, v162
	v_mul_f32_e32 v28, v20, v28
	v_mul_f32_e32 v29, v21, v29
	v_mul_f32_e32 v30, v22, v30
	v_mul_f32_e32 v31, v23, v31
	v_mul_f32_e32 v24, v16, v24
	v_mul_f32_e32 v25, v17, v25
	v_mul_f32_e32 v26, v18, v26
	v_mul_f32_e32 v27, v19, v27
	v_mul_f32_e32 v20, v20, v232
	v_mul_f32_e32 v21, v21, v232
	v_mul_f32_e32 v22, v22, v232
	v_mul_f32_e32 v23, v23, v232
	v_mul_f32_e32 v16, v16, v232
	v_mul_f32_e32 v17, v17, v232
	v_mul_f32_e32 v18, v18, v232
	v_mul_f32_e32 v19, v19, v232
	v_exp_f32_e32 v20, v20
	v_exp_f32_e32 v21, v21
	v_exp_f32_e32 v22, v22
	v_exp_f32_e32 v23, v23
	v_exp_f32_e32 v16, v16
	v_exp_f32_e32 v17, v17
	v_exp_f32_e32 v18, v18
	v_exp_f32_e32 v19, v19
	v_add_f32_e32 v20, 1.0, v20
	v_add_f32_e32 v21, 1.0, v21
	v_add_f32_e32 v22, 1.0, v22
	v_add_f32_e32 v23, 1.0, v23
	v_add_f32_e32 v16, 1.0, v16
	v_add_f32_e32 v17, 1.0, v17
	v_add_f32_e32 v18, 1.0, v18
	v_add_f32_e32 v19, 1.0, v19
	v_rcp_f32_e32 v20, v20
	v_rcp_f32_e32 v21, v21
	v_rcp_f32_e32 v22, v22
	v_rcp_f32_e32 v23, v23
	v_rcp_f32_e32 v16, v16
	v_rcp_f32_e32 v17, v17
	v_rcp_f32_e32 v18, v18
	v_rcp_f32_e32 v19, v19
	v_mul_f32_e32 v28, v28, v240
	v_mul_f32_e32 v29, v29, v240
	v_mul_f32_e32 v30, v30, v240
	v_mul_f32_e32 v31, v31, v240
	v_mul_f32_e32 v24, v24, v240
	v_mul_f32_e32 v25, v25, v240
	v_mul_f32_e32 v26, v26, v240
	v_mul_f32_e32 v27, v27, v240
	v_mul_f32_e32 v28, v28, v20
	v_mul_f32_e32 v29, v29, v21
	v_mul_f32_e32 v30, v30, v22
	v_mul_f32_e32 v31, v31, v23
	v_mul_f32_e32 v24, v24, v16
	v_mul_f32_e32 v25, v25, v17
	v_mul_f32_e32 v26, v26, v18
	v_mul_f32_e32 v27, v27, v19
	v_cvt_pk_bf16_f32 v20, v28, v29
	v_cvt_pk_bf16_f32 v21, v30, v31
	v_cvt_pk_bf16_f32 v22, v24, v25
	v_cvt_pk_bf16_f32 v23, v26, v27
	global_store_dwordx4 v164, v[20:23], s[10:11]
	v_add_u32_e32 v165, 0x1e4000, v162
	v_mul_f32_e32 v12, v8, v12
	v_mul_f32_e32 v13, v9, v13
	v_mul_f32_e32 v14, v10, v14
	v_mul_f32_e32 v15, v11, v15
	v_mul_f32_e32 v0, v4, v0
	v_mul_f32_e32 v1, v5, v1
	v_mul_f32_e32 v2, v6, v2
	v_mul_f32_e32 v3, v7, v3
	v_mul_f32_e32 v8, v8, v233
	v_mul_f32_e32 v9, v9, v233
	v_mul_f32_e32 v10, v10, v233
	v_mul_f32_e32 v11, v11, v233
	v_mul_f32_e32 v4, v4, v233
	v_mul_f32_e32 v5, v5, v233
	v_mul_f32_e32 v6, v6, v233
	v_mul_f32_e32 v7, v7, v233
	v_exp_f32_e32 v8, v8
	v_exp_f32_e32 v9, v9
	v_exp_f32_e32 v10, v10
	v_exp_f32_e32 v11, v11
	v_exp_f32_e32 v4, v4
	v_exp_f32_e32 v5, v5
	v_exp_f32_e32 v6, v6
	v_exp_f32_e32 v7, v7
	v_add_f32_e32 v8, 1.0, v8
	v_add_f32_e32 v9, 1.0, v9
	v_add_f32_e32 v10, 1.0, v10
	v_add_f32_e32 v11, 1.0, v11
	v_add_f32_e32 v4, 1.0, v4
	v_add_f32_e32 v5, 1.0, v5
	v_add_f32_e32 v6, 1.0, v6
	v_add_f32_e32 v7, 1.0, v7
	v_rcp_f32_e32 v8, v8
	v_rcp_f32_e32 v9, v9
	v_rcp_f32_e32 v10, v10
	v_rcp_f32_e32 v11, v11
	v_rcp_f32_e32 v4, v4
	v_rcp_f32_e32 v5, v5
	v_rcp_f32_e32 v6, v6
	v_rcp_f32_e32 v7, v7
	v_mul_f32_e32 v12, v12, v241
	v_mul_f32_e32 v13, v13, v241
	v_mul_f32_e32 v14, v14, v241
	v_mul_f32_e32 v15, v15, v241
	v_mul_f32_e32 v0, v0, v241
	v_mul_f32_e32 v1, v1, v241
	v_mul_f32_e32 v2, v2, v241
	v_mul_f32_e32 v3, v3, v241
	v_mul_f32_e32 v12, v12, v8
	v_mul_f32_e32 v13, v13, v9
	v_mul_f32_e32 v14, v14, v10
	v_mul_f32_e32 v15, v15, v11
	v_mul_f32_e32 v0, v0, v4
	v_mul_f32_e32 v1, v1, v5
	v_mul_f32_e32 v2, v2, v6
	v_mul_f32_e32 v3, v3, v7
	v_cvt_pk_bf16_f32 v8, v12, v13
	v_cvt_pk_bf16_f32 v9, v14, v15
	v_cvt_pk_bf16_f32 v10, v0, v1
	v_cvt_pk_bf16_f32 v11, v2, v3
	global_store_dwordx4 v165, v[8:11], s[10:11]
	s_andn2_b64 vcc, exec, s[8:9]
	s_mov_b64 s[8:9], -1
	s_cbranch_vccnz .LBB0_1283
	s_and_b64 vcc, exec, s[66:67]
	s_cbranch_vccnz .LBB0_1282
	s_barrier
	s_branch .LBB0_1282
